# step A: its 24 global loads issued at the top of the task loop (before wave 0's step 0 and the barrier)
# baseline (speedup 1.0000x reference)
; #define LAS __attribute__((address_space(3)))
; __device__ __forceinline__ float exp_f(float x) { return __builtin_amdgcn_exp2f(x * 1.4426950408889634f); }
; __device__ __forceinline__ float sigmoid_f(float x) { return rcp_f(1.f + exp_f(-x)); }
; __device__ __forceinline__ float softplus_f(float x) { return fmaxf(x, 0.f) + __logf(1.f + exp_f(-fabsf(x))); }
; __device__ __forceinline__ void prep_task(LAS unsigned char* lds, const PrepP& P, int task, int tid, int lane, int wave) {
;     ...
;     if (wave == 0) {
;         const float* bar = P.ba + (size_t)(row0 + lane) * 16;
;         float g = -exp_f(P.alog[h]) * softplus_f(bar[8 + h] + P.dtb[h]);
; #pragma unroll
;         for (int o = 1; o < 64; o <<= 1) { const float v = __shfl_up(g, o); if (lane >= o) g += v; }
;         gcl[lane] = g; gcl[64 + lane] = sigmoid_f(bar[h]);
;         if (lane == 63) P.gl[task] = exp_f(g);
;     }
;     ...
;         const int t = tid >> 3, seg = tid & 7;
;         const float beta = gcl[64 + t], gc = gcl[t], glc = gcl[63];
;         const float eg = exp_f(gc), et = exp_f(glc - gc);
;         const int tt = n * 64 + t;
;         const bf16_t* zr = P.z + (size_t)(row0 + t) * NZ + 4096 + h * 128 + seg * 16;
;         const LAS float* cw = (const LAS float*)(lds + 114688) + seg * 16;
;         u32x4 xz[3][2][4];
; #pragma unroll
;         for (int m = 0; m < 3; ++m)
; #pragma unroll
;             for (int hf = 0; hf < 2; ++hf)
; #pragma unroll
;                 for (int j = 0; j < 4; ++j) { const bool ok = tt - 3 + j >= 0; xz[m][hf][j] = *(const u32x4*)(zr + m * 1024 + hf * 8 + (ptrdiff_t)(ok ? j - 3 : 0) * NZ); if (!ok) xz[m][hf][j] = (u32x4){0u, 0u, 0u, 0u}; }
.LBB0_416:
	v_mov_b32_e32 v55, v54
	v_mov_b32_e32 v48, 0
	s_and_b32 s8, s49, 0xffffffc0
	v_and_b32_e32 v0, -16, v48
	v_add_u32_e32 v58, 0, v0
	v_cndmask_b32_e64 v0, 0, 1, s[16:17]
	v_and_b32_e32 v56, 63, v55
	v_add_u32_e32 v63, 0x1b800, v58
	v_cmp_ne_u32_e64 s[4:5], 1, v0
	s_load_dwordx2 s[98:99], s[0:1], 0x98
	s_lshr_b32 s101, s49, 11
	s_lshr_b32 s100, s2, 3
	s_and_b32 s100, s100, 31
	s_lshl_b32 s15, s101, 11
	s_lshl_b32 s10, s100, 6
	s_add_i32 s15, s15, s10
	v_ashrrev_i32_e32 v26, 3, v55
	v_add_u32_e32 v27, s10, v26
	v_add_u32_e32 v57, s15, v26
	v_and_b32_e32 v28, 7, v55
	v_lshlrev_b32_e32 v57, 14, v57
	s_and_b32 s15, s2, 7
	s_lshl_b32 s15, s15, 8
	s_addk_i32 s15, 0x2800
	v_lshl_add_u32 v29, v28, 5, s15
	v_add_u32_e32 v57, v57, v29
	v_min_u32_e32 v59, 3, v27
	v_lshlrev_b32_e32 v59, 14, v59
	v_sub_u32_e32 v59, v57, v59
	v_min_u32_e32 v61, 2, v27
	v_lshlrev_b32_e32 v61, 14, v61
	v_sub_u32_e32 v61, v57, v61
	v_min_u32_e32 v62, 1, v27
	v_lshlrev_b32_e32 v62, 14, v62
	v_sub_u32_e32 v62, v57, v62
	s_waitcnt lgkmcnt(0)
	s_add_u32 s98, s98, 0x13c00000
	s_addc_u32 s99, s99, 0
	global_load_dwordx4 v[64:67], v59, s[98:99] offset:-2048
	global_load_dwordx4 v[80:83], v59, s[98:99] offset:-2032
	global_load_dwordx4 v[96:99], v59, s[98:99]
	global_load_dwordx4 v[112:115], v59, s[98:99] offset:16
	global_load_dwordx4 v[128:131], v59, s[98:99] offset:2048
	global_load_dwordx4 v[144:147], v59, s[98:99] offset:2064
	global_load_dwordx4 v[68:71], v61, s[98:99] offset:-2048
	global_load_dwordx4 v[84:87], v61, s[98:99] offset:-2032
	global_load_dwordx4 v[100:103], v61, s[98:99]
	global_load_dwordx4 v[116:119], v61, s[98:99] offset:16
	global_load_dwordx4 v[132:135], v61, s[98:99] offset:2048
	global_load_dwordx4 v[148:151], v61, s[98:99] offset:2064
	global_load_dwordx4 v[72:75], v62, s[98:99] offset:-2048
	global_load_dwordx4 v[88:91], v62, s[98:99] offset:-2032
	global_load_dwordx4 v[104:107], v62, s[98:99]
	global_load_dwordx4 v[120:123], v62, s[98:99] offset:16
	global_load_dwordx4 v[136:139], v62, s[98:99] offset:2048
	global_load_dwordx4 v[156:159], v62, s[98:99] offset:2064
	global_load_dwordx4 v[76:79], v57, s[98:99] offset:-2048
	global_load_dwordx4 v[92:95], v57, s[98:99] offset:-2032
	global_load_dwordx4 v[108:111], v57, s[98:99]
	global_load_dwordx4 v[124:127], v57, s[98:99] offset:16
	global_load_dwordx4 v[140:143], v57, s[98:99] offset:2048
	global_load_dwordx4 v[160:163], v57, s[98:99] offset:2064
	s_andn2_b64 vcc, exec, s[16:17]
	s_cbranch_vccnz .LBB0_420
	v_or_b32_e32 v0, s8, v56
	v_ashrrev_i32_e32 v1, 31, v0
	v_lshlrev_b64 v[0:1], 6, v[0:1]
	v_lshl_add_u64 v[0:1], v[44:45], 0, v[0:1]
	global_load_dword v2, v[46:47], off
	global_load_dword v3, v[0:1], off offset:32
	global_load_dword v4, v[42:43], off
	s_nop 0
	global_load_dword v0, v[0:1], off
	v_and_b32_e32 v1, 64, v192
	v_add_u32_e32 v5, -1, v192
	v_cmp_lt_i32_e32 vcc, v5, v1
	v_add_u32_e32 v6, -2, v192
	s_waitcnt vmcnt(2)
	v_add_f32_e32 v2, v3, v2
	v_mul_f32_e64 v3, |v2|, s81
	v_exp_f32_e32 v3, v3
	v_cndmask_b32_e32 v5, v5, v192, vcc
	s_waitcnt vmcnt(1)
	v_mul_f32_e32 v4, 0x3fb8aa3b, v4
	v_exp_f32_e32 v4, v4
	v_add_f32_e32 v3, 1.0, v3
	v_cmp_gt_f32_e32 vcc, s82, v3
	v_max_f32_e32 v2, 0, v2
	v_lshlrev_b32_e32 v5, 2, v5
	v_cndmask_b32_e64 v7, 0, 32, vcc
	v_ldexp_f32 v3, v3, v7
	v_log_f32_e32 v3, v3
	v_cndmask_b32_e32 v7, 0, v196, vcc
	s_waitcnt vmcnt(0)
	v_mul_f32_e32 v0, 0xbfb8aa3b, v0
	v_exp_f32_e32 v0, v0
	v_mul_f32_e32 v8, 0x3f317217, v3
	v_fma_f32 v8, v3, s83, -v8
	v_fmac_f32_e32 v8, 0x3377d1cf, v3
	v_fmac_f32_e32 v8, 0x3f317217, v3
	v_cmp_lt_f32_e64 vcc, |v3|, s97
	v_add_f32_e32 v0, 1.0, v0
	s_nop 0
	v_cndmask_b32_e32 v3, v3, v8, vcc
	v_sub_f32_e32 v3, v3, v7
	v_add_f32_e32 v2, v2, v3
	v_mul_f32_e64 v3, v2, -v4
	ds_bpermute_b32 v5, v5, v3
	v_cmp_lt_i32_e32 vcc, v6, v1
	v_add_u32_e32 v7, -4, v192
	s_waitcnt lgkmcnt(0)
	v_fma_f32 v2, v2, -v4, v5
	v_cndmask_b32_e32 v6, v6, v192, vcc
	v_cmp_eq_u32_e32 vcc, 0, v56
	v_lshlrev_b32_e32 v6, 2, v6
	v_add_u32_e32 v4, -8, v192
	v_cndmask_b32_e32 v2, v2, v3, vcc
	ds_bpermute_b32 v3, v6, v2
	v_cmp_lt_i32_e32 vcc, v7, v1
	s_waitcnt lgkmcnt(0)
	v_add_f32_e32 v3, v2, v3
	v_cndmask_b32_e32 v5, v7, v192, vcc
	v_cmp_gt_u32_e32 vcc, 2, v56
	v_lshlrev_b32_e32 v5, 2, v5
	s_nop 0
	v_cndmask_b32_e32 v2, v3, v2, vcc
	ds_bpermute_b32 v3, v5, v2
	v_cmp_lt_i32_e32 vcc, v4, v1
	v_add_u32_e32 v5, -16, v192
	s_waitcnt lgkmcnt(0)
	v_add_f32_e32 v3, v2, v3
	v_cndmask_b32_e32 v4, v4, v192, vcc
	v_cmp_gt_u32_e32 vcc, 4, v56
	v_lshlrev_b32_e32 v4, 2, v4
	s_nop 0
	v_cndmask_b32_e32 v2, v3, v2, vcc
	ds_bpermute_b32 v3, v4, v2
	v_cmp_lt_i32_e32 vcc, v5, v1
	v_subrev_u32_e32 v4, 32, v192
	s_waitcnt lgkmcnt(0)
	v_add_f32_e32 v3, v2, v3
	v_cndmask_b32_e32 v5, v5, v192, vcc
	v_cmp_gt_u32_e32 vcc, 8, v56
	v_lshlrev_b32_e32 v5, 2, v5
	s_nop 0
	v_cndmask_b32_e32 v2, v3, v2, vcc
	ds_bpermute_b32 v3, v5, v2
	v_cmp_lt_i32_e32 vcc, v4, v1
	s_waitcnt lgkmcnt(0)
	v_add_f32_e32 v3, v2, v3
	v_cndmask_b32_e32 v1, v4, v192, vcc
	v_cmp_gt_u32_e32 vcc, 16, v56
	v_lshlrev_b32_e32 v1, 2, v1
	v_rcp_f32_e32 v4, v0
	v_cndmask_b32_e32 v2, v3, v2, vcc
	ds_bpermute_b32 v1, v1, v2
	v_cmp_gt_u32_e32 vcc, 32, v56
	v_lshl_add_u32 v3, v56, 2, v63
	s_waitcnt lgkmcnt(0)
	v_add_f32_e32 v0, v2, v1
	v_cndmask_b32_e32 v1, v0, v2, vcc
	v_cmp_eq_u32_e32 vcc, 63, v56
	ds_write2st64_b32 v3, v1, v4 offset1:1
	s_and_saveexec_b64 s[6:7], vcc
	s_cbranch_execz .LBB0_419
	v_mul_f32_e32 v0, 0x3fb8aa3b, v0
	v_exp_f32_e32 v0, v0
	v_lshl_add_u64 v[2:3], v[40:41], 0, s[24:25]
	global_store_dword v[2:3], v0, off

; #define LAS __attribute__((address_space(3)))
; __device__ __forceinline__ float exp_f(float x) { return __builtin_amdgcn_exp2f(x * 1.4426950408889634f); }
; #define LBAR() do { asm volatile("s_waitcnt lgkmcnt(0)" ::: "memory"); __builtin_amdgcn_s_barrier(); asm volatile("" ::: "memory"); } while (0)
; __device__ __forceinline__ void prep_task(LAS unsigned char* lds, const PrepP& P, int task, int tid, int lane, int wave) {
;     ...
;     LBAR();
;     {
;         const int t = tid >> 3, seg = tid & 7;
;         const float beta = gcl[64 + t], gc = gcl[t], glc = gcl[63];
;         const float eg = exp_f(gc), et = exp_f(glc - gc);
;         const int tt = n * 64 + t;
;         const bf16_t* zr = P.z + (size_t)(row0 + t) * NZ + 4096 + h * 128 + seg * 16;
;         const LAS float* cw = (const LAS float*)(lds + 114688) + seg * 16;
;         u32x4 xz[3][2][4];
; #pragma unroll
;         for (int m = 0; m < 3; ++m)
; #pragma unroll
;             for (int hf = 0; hf < 2; ++hf)
; #pragma unroll
;                 for (int j = 0; j < 4; ++j) { const bool ok = tt - 3 + j >= 0; xz[m][hf][j] = *(const u32x4*)(zr + m * 1024 + hf * 8 + (ptrdiff_t)(ok ? j - 3 : 0) * NZ); if (!ok) xz[m][hf][j] = (u32x4){0u, 0u, 0u, 0u}; }
;         const int lo = t * PS + seg * 16;
;         float x[16], y[16];
;         { float o[8]; conv8(xz[2][0], cw + 256, o);
.LBB0_420:
	v_ashrrev_i32_e32 v26, 3, v55
	v_add_u32_e32 v0, s8, v26
	v_ashrrev_i32_e32 v1, 31, v0
	v_lshlrev_b64 v[0:1], 14, v[0:1]
	v_lshlrev_b32_e32 v2, 4, v55
	v_lshl_add_u64 v[0:1], v[40:41], 0, v[0:1]
	v_and_b32_e32 v60, 0x70, v2
	v_lshl_add_u64 v[0:1], v[0:1], 0, s[38:39]
	v_lshlrev_b32_e32 v152, 1, v60
	v_lshl_add_u64 v[4:5], v[0:1], 0, v[152:153]
	s_mov_b64 s[6:7], 0x13c02000
	s_and_b32 s9, s49, 0x7c0
	v_lshl_add_u64 v[6:7], v[4:5], 0, s[6:7]
	v_add_co_u32_e64 v12, s[6:7], s76, v4
	v_add_u32_e32 v27, s9, v26
	s_nop 0
	v_addc_co_u32_e64 v13, s[6:7], 0, v5, s[6:7]
	v_cmp_lt_i32_e32 vcc, 2, v27
	v_mov_b32_e32 v0, 0xffff4000
	v_cmp_lt_i32_e64 s[6:7], 0, v27
	v_cndmask_b32_e32 v8, 0, v0, vcc
	v_cmp_lt_i32_e64 s[8:9], 1, v27
	v_cndmask_b32_e64 v0, 0, -1, s[6:7]
	v_mov_b32_e32 v1, v0
	s_mov_b64 s[10:11], 0x13c03000
	v_cndmask_b32_e64 v9, 0, -1, vcc
	v_cndmask_b32_e64 v15, 0, -1, s[8:9]
	v_cndmask_b32_e64 v14, 0, v197, s[8:9]
	v_lshlrev_b64 v[24:25], 14, v[0:1]
	v_lshl_add_u64 v[32:33], v[4:5], 0, s[10:11]
	s_waitcnt lgkmcnt(0)
	s_barrier
	v_and_b32_e32 v28, 7, v55
	v_lshl_add_u32 v36, v28, 6, v58
	v_add_u32_e32 v36, 0x1c000, v36
	v_mul_u32_u24_e32 v37, 0x110, v26
	v_lshl_add_u32 v37, v28, 5, v37
	v_add_u32_e32 v37, v37, v58
	v_add_u32_e32 v38, 0xcc00, v37
	v_lshlrev_b32_e32 v39, 8, v26
	v_lshl_add_u32 v39, v28, 5, v39
	v_lshl_add_u32 v30, v26, 2, v63
	v_add_u32_e32 v31, 0x1b8fc, v58
	ds_read2st64_b32 v[32:33], v30 offset1:1
	ds_read_b32 v53, v31
	s_waitcnt lgkmcnt(0)
	s_lshl_b32 s15, s101, 8
	s_add_i32 s15, s15, s2
	s_mul_hi_u32 s9, s15, 0x1a000
	s_mul_i32 s8, s15, 0x1a000
	s_add_u32 s8, s8, s98
	s_addc_u32 s9, s9, s99
	s_add_u32 s8, s8, 0xe804000
	s_addc_u32 s9, s9, 0
	s_mov_b32 s10, 0xffff0000
	v_mov_b32_e32 v252, 0xbfb8aa3b
	v_mov_b32_e32 v253, 0xbfb8aa3b
	s_mov_b32 s14, 1.0
	s_mov_b32 s15, 1.0
	v_mov_b32_e32 v51, v32
	v_mov_b32_e32 v50, v33
	v_sub_f32_e32 v24, v53, v51
	v_mul_f32_e32 v52, 0x3fb8aa3b, v51
	v_mul_f32_e32 v24, 0x3fb8aa3b, v24
	v_exp_f32_e32 v52, v52
	v_exp_f32_e32 v24, v24
	s_nop 0
	v_mul_f32_e32 v62, v50, v52
	ds_read_b128 v[164:167], v36 offset:1024
	ds_read_b128 v[168:171], v36 offset:1040
	ds_read_b128 v[172:175], v36 offset:2560
	ds_read_b128 v[176:179], v36 offset:2576
	ds_read_b128 v[180:183], v36 offset:4096
	ds_read_b128 v[184:187], v36 offset:4112
	ds_read_b128 v[188:191], v36 offset:5632
	ds_read_b128 v[200:203], v36 offset:5648
	s_waitcnt vmcnt(0)
	s_cmp_lg_u32 s100, 0
	s_cbranch_scc1 .Lstepa_nomask
	v_cmp_gt_u32_e32 vcc, 3, v27
	s_nop 1
	v_cndmask_b32_e64 v64, v64, 0, vcc
	v_cndmask_b32_e64 v65, v65, 0, vcc
	v_cndmask_b32_e64 v66, v66, 0, vcc
	v_cndmask_b32_e64 v67, v67, 0, vcc
	v_cndmask_b32_e64 v80, v80, 0, vcc
	v_cndmask_b32_e64 v81, v81, 0, vcc
	v_cndmask_b32_e64 v82, v82, 0, vcc
	v_cndmask_b32_e64 v83, v83, 0, vcc
	v_cndmask_b32_e64 v96, v96, 0, vcc
	v_cndmask_b32_e64 v97, v97, 0, vcc
	v_cndmask_b32_e64 v98, v98, 0, vcc
	v_cndmask_b32_e64 v99, v99, 0, vcc
	v_cndmask_b32_e64 v112, v112, 0, vcc
	v_cndmask_b32_e64 v113, v113, 0, vcc
	v_cndmask_b32_e64 v114, v114, 0, vcc
	v_cndmask_b32_e64 v115, v115, 0, vcc
	v_cndmask_b32_e64 v128, v128, 0, vcc
	v_cndmask_b32_e64 v129, v129, 0, vcc
	v_cndmask_b32_e64 v130, v130, 0, vcc
	v_cndmask_b32_e64 v131, v131, 0, vcc
	v_cndmask_b32_e64 v144, v144, 0, vcc
	v_cndmask_b32_e64 v145, v145, 0, vcc
	v_cndmask_b32_e64 v146, v146, 0, vcc
	v_cndmask_b32_e64 v147, v147, 0, vcc
	v_cmp_gt_u32_e32 vcc, 2, v27
	s_nop 1
	v_cndmask_b32_e64 v68, v68, 0, vcc
	v_cndmask_b32_e64 v69, v69, 0, vcc
	v_cndmask_b32_e64 v70, v70, 0, vcc
	v_cndmask_b32_e64 v71, v71, 0, vcc
	v_cndmask_b32_e64 v84, v84, 0, vcc
	v_cndmask_b32_e64 v85, v85, 0, vcc
	v_cndmask_b32_e64 v86, v86, 0, vcc
	v_cndmask_b32_e64 v87, v87, 0, vcc
	v_cndmask_b32_e64 v100, v100, 0, vcc
	v_cndmask_b32_e64 v101, v101, 0, vcc
	v_cndmask_b32_e64 v102, v102, 0, vcc
	v_cndmask_b32_e64 v103, v103, 0, vcc
	v_cndmask_b32_e64 v116, v116, 0, vcc
	v_cndmask_b32_e64 v117, v117, 0, vcc
	v_cndmask_b32_e64 v118, v118, 0, vcc
	v_cndmask_b32_e64 v119, v119, 0, vcc
	v_cndmask_b32_e64 v132, v132, 0, vcc
	v_cndmask_b32_e64 v133, v133, 0, vcc
	v_cndmask_b32_e64 v134, v134, 0, vcc
	v_cndmask_b32_e64 v135, v135, 0, vcc
	v_cndmask_b32_e64 v148, v148, 0, vcc
	v_cndmask_b32_e64 v149, v149, 0, vcc
	v_cndmask_b32_e64 v150, v150, 0, vcc
	v_cndmask_b32_e64 v151, v151, 0, vcc
	v_cmp_gt_u32_e32 vcc, 1, v27
	s_nop 1
	v_cndmask_b32_e64 v72, v72, 0, vcc
	v_cndmask_b32_e64 v73, v73, 0, vcc
	v_cndmask_b32_e64 v74, v74, 0, vcc
	v_cndmask_b32_e64 v75, v75, 0, vcc
	v_cndmask_b32_e64 v88, v88, 0, vcc
	v_cndmask_b32_e64 v89, v89, 0, vcc
	v_cndmask_b32_e64 v90, v90, 0, vcc
	v_cndmask_b32_e64 v91, v91, 0, vcc
	v_cndmask_b32_e64 v104, v104, 0, vcc
	v_cndmask_b32_e64 v105, v105, 0, vcc
	v_cndmask_b32_e64 v106, v106, 0, vcc
	v_cndmask_b32_e64 v107, v107, 0, vcc
	v_cndmask_b32_e64 v120, v120, 0, vcc
	v_cndmask_b32_e64 v121, v121, 0, vcc
	v_cndmask_b32_e64 v122, v122, 0, vcc
	v_cndmask_b32_e64 v123, v123, 0, vcc
	v_cndmask_b32_e64 v136, v136, 0, vcc
	v_cndmask_b32_e64 v137, v137, 0, vcc
	v_cndmask_b32_e64 v138, v138, 0, vcc
	v_cndmask_b32_e64 v139, v139, 0, vcc
	v_cndmask_b32_e64 v156, v156, 0, vcc
	v_cndmask_b32_e64 v157, v157, 0, vcc
	v_cndmask_b32_e64 v158, v158, 0, vcc
	v_cndmask_b32_e64 v159, v159, 0, vcc
